# v71 + EpiFinal part 2 hand-written (gn vectors and rstd loaded once; no per-piece vmcnt(0) waits)
# baseline (speedup 1.0000x reference)
;     DI void operator()(f32x4 (&acc)[2][2][4][2], const pg8::Unit& u, int wr, int wc, int fr, int fq) const {
;     ...
;         asm volatile("s_waitcnt vmcnt(0) lgkmcnt(0)" ::: "memory"); __builtin_amdgcn_s_barrier(); asm volatile("" ::: "memory");
;         if (tid < 256) { const float* sl = slots + ((size_t)u.pm * 256 + tid) * 4; float tot = 0.f;
; #pragma unroll
;             for (int t = 0; t < 4; ++t) tot += __hip_atomic_load(sl + t, __ATOMIC_RELAXED, __HIP_MEMORY_SCOPE_AGENT);
;             X[1024 + tid] = rsqrtf(tot * (1.0f / DM) + EPS); }
;         asm volatile("s_waitcnt vmcnt(0) lgkmcnt(0)" ::: "memory"); __builtin_amdgcn_s_barrier(); asm volatile("" ::: "memory");
; #pragma unroll
;         for (int ai = 0; ai < 2; ++ai)
; #pragma unroll
;             for (int m = 0; m < 4; ++m) { const int rl = ai * 128 + wr * 64 + m * 16 + fr; const float rs = X[1024 + rl]; float* orow = yout + ((size_t)u.pm * 256 + rl) * DM;
; #pragma unroll
;                 for (int bj = 0; bj < 2; ++bj)
; #pragma unroll
;                     for (int n = 0; n < 2; ++n) { const int col = col0 + bj * 128 + n * 16;
;                         __builtin_nontemporal_store(acc[ai][bj][m][n] * rs * *(const f32x4*)(gn + col), (f32x4*)(orow + col)); }
;                 asm volatile("" ::: "memory"); }
.LBB0_2234:
	s_or_b64 exec, exec, s[42:43]
	v_lshlrev_b64 v[158:159], 2, v[156:157]
	s_waitcnt vmcnt(0) lgkmcnt(0)
	s_barrier
	v_lshl_add_u64 v[156:157], s[50:51], 0, v[158:159]
	global_load_dwordx4 v[190:193], v[156:157], off
	global_load_dwordx4 v[194:197], v[156:157], off offset:64
	global_load_dwordx4 v[198:201], v[156:157], off offset:512
	global_load_dwordx4 v[202:205], v[156:157], off offset:576
	v_and_b32_e32 v248, 15, v226
	v_lshrrev_b32_e32 v249, 8, v226
	v_lshl_or_b32 v248, v249, 6, v248
	v_lshl_add_u32 v248, v248, 2, s62
	ds_read_b32 v210, v248 offset:4096
	ds_read_b32 v212, v248 offset:4160
	ds_read_b32 v214, v248 offset:4224
	ds_read_b32 v216, v248 offset:4288
	ds_read_b32 v218, v248 offset:4608
	ds_read_b32 v220, v248 offset:4672
	ds_read_b32 v222, v248 offset:4736
	ds_read_b32 v224, v248 offset:4800
	v_lshlrev_b64 v[160:161], 20, v[160:161]
	v_lshl_add_u64 v[160:161], s[24:25], 0, v[160:161]
	v_lshl_add_u64 v[168:169], v[160:161], 0, v[132:133]
	v_lshl_add_u64 v[168:169], v[168:169], 0, v[158:159]
	s_mov_b32 s16, 0x10000
	s_mov_b32 s17, 0
	s_waitcnt vmcnt(0) lgkmcnt(0)
	v_pk_mul_f32 v[126:127], v[126:127], v[210:211] op_sel_hi:[1,0]
	v_pk_mul_f32 v[124:125], v[124:125], v[210:211] op_sel_hi:[1,0]
	v_pk_mul_f32 v[126:127], v[192:193], v[126:127]
	v_pk_mul_f32 v[124:125], v[190:191], v[124:125]
	global_store_dwordx4 v[168:169], v[124:127], off nt
	v_pk_mul_f32 v[122:123], v[122:123], v[210:211] op_sel_hi:[1,0]
	v_pk_mul_f32 v[120:121], v[120:121], v[210:211] op_sel_hi:[1,0]
	v_pk_mul_f32 v[122:123], v[196:197], v[122:123]
	v_pk_mul_f32 v[120:121], v[194:195], v[120:121]
	global_store_dwordx4 v[168:169], v[120:123], off offset:64 nt
	v_pk_mul_f32 v[118:119], v[118:119], v[210:211] op_sel_hi:[1,0]
	v_pk_mul_f32 v[116:117], v[116:117], v[210:211] op_sel_hi:[1,0]
	v_pk_mul_f32 v[118:119], v[200:201], v[118:119]
	v_pk_mul_f32 v[116:117], v[198:199], v[116:117]
	global_store_dwordx4 v[168:169], v[116:119], off offset:512 nt
	v_pk_mul_f32 v[114:115], v[114:115], v[210:211] op_sel_hi:[1,0]
	v_pk_mul_f32 v[112:113], v[112:113], v[210:211] op_sel_hi:[1,0]
	v_pk_mul_f32 v[114:115], v[204:205], v[114:115]
	v_pk_mul_f32 v[112:113], v[202:203], v[112:113]
	global_store_dwordx4 v[168:169], v[112:115], off offset:576 nt
	v_lshl_add_u64 v[168:169], v[168:169], 0, s[16:17]
	v_pk_mul_f32 v[110:111], v[110:111], v[212:213] op_sel_hi:[1,0]
	v_pk_mul_f32 v[108:109], v[108:109], v[212:213] op_sel_hi:[1,0]
	v_pk_mul_f32 v[110:111], v[192:193], v[110:111]
	v_pk_mul_f32 v[108:109], v[190:191], v[108:109]
	global_store_dwordx4 v[168:169], v[108:111], off nt
	v_pk_mul_f32 v[106:107], v[106:107], v[212:213] op_sel_hi:[1,0]
	v_pk_mul_f32 v[104:105], v[104:105], v[212:213] op_sel_hi:[1,0]
	v_pk_mul_f32 v[106:107], v[196:197], v[106:107]
	v_pk_mul_f32 v[104:105], v[194:195], v[104:105]
	global_store_dwordx4 v[168:169], v[104:107], off offset:64 nt
	v_pk_mul_f32 v[102:103], v[102:103], v[212:213] op_sel_hi:[1,0]
	v_pk_mul_f32 v[100:101], v[100:101], v[212:213] op_sel_hi:[1,0]
	v_pk_mul_f32 v[102:103], v[200:201], v[102:103]
	v_pk_mul_f32 v[100:101], v[198:199], v[100:101]
	global_store_dwordx4 v[168:169], v[100:103], off offset:512 nt
	v_pk_mul_f32 v[98:99], v[98:99], v[212:213] op_sel_hi:[1,0]
	v_pk_mul_f32 v[96:97], v[96:97], v[212:213] op_sel_hi:[1,0]
	v_pk_mul_f32 v[98:99], v[204:205], v[98:99]
	v_pk_mul_f32 v[96:97], v[202:203], v[96:97]
	global_store_dwordx4 v[168:169], v[96:99], off offset:576 nt
	v_lshl_add_u64 v[168:169], v[168:169], 0, s[16:17]
	v_pk_mul_f32 v[94:95], v[94:95], v[214:215] op_sel_hi:[1,0]
	v_pk_mul_f32 v[92:93], v[92:93], v[214:215] op_sel_hi:[1,0]
	v_pk_mul_f32 v[94:95], v[192:193], v[94:95]
	v_pk_mul_f32 v[92:93], v[190:191], v[92:93]
	global_store_dwordx4 v[168:169], v[92:95], off nt
	v_pk_mul_f32 v[90:91], v[90:91], v[214:215] op_sel_hi:[1,0]
	v_pk_mul_f32 v[88:89], v[88:89], v[214:215] op_sel_hi:[1,0]
	v_pk_mul_f32 v[90:91], v[196:197], v[90:91]
	v_pk_mul_f32 v[88:89], v[194:195], v[88:89]
	global_store_dwordx4 v[168:169], v[88:91], off offset:64 nt
	v_pk_mul_f32 v[86:87], v[86:87], v[214:215] op_sel_hi:[1,0]
	v_pk_mul_f32 v[84:85], v[84:85], v[214:215] op_sel_hi:[1,0]
	v_pk_mul_f32 v[86:87], v[200:201], v[86:87]
	v_pk_mul_f32 v[84:85], v[198:199], v[84:85]
	global_store_dwordx4 v[168:169], v[84:87], off offset:512 nt
	v_pk_mul_f32 v[82:83], v[82:83], v[214:215] op_sel_hi:[1,0]
	v_pk_mul_f32 v[80:81], v[80:81], v[214:215] op_sel_hi:[1,0]
	v_pk_mul_f32 v[82:83], v[204:205], v[82:83]
	v_pk_mul_f32 v[80:81], v[202:203], v[80:81]
	global_store_dwordx4 v[168:169], v[80:83], off offset:576 nt
	v_lshl_add_u64 v[168:169], v[168:169], 0, s[16:17]
	v_pk_mul_f32 v[78:79], v[78:79], v[216:217] op_sel_hi:[1,0]
	v_pk_mul_f32 v[76:77], v[76:77], v[216:217] op_sel_hi:[1,0]
	v_pk_mul_f32 v[78:79], v[192:193], v[78:79]
	v_pk_mul_f32 v[76:77], v[190:191], v[76:77]
	global_store_dwordx4 v[168:169], v[76:79], off nt
	v_pk_mul_f32 v[74:75], v[74:75], v[216:217] op_sel_hi:[1,0]
	v_pk_mul_f32 v[72:73], v[72:73], v[216:217] op_sel_hi:[1,0]
	v_pk_mul_f32 v[74:75], v[196:197], v[74:75]
	v_pk_mul_f32 v[72:73], v[194:195], v[72:73]
	global_store_dwordx4 v[168:169], v[72:75], off offset:64 nt
	v_pk_mul_f32 v[70:71], v[70:71], v[216:217] op_sel_hi:[1,0]
;     DI void operator()(f32x4 (&acc)[2][2][4][2], const pg8::Unit& u, int wr, int wc, int fr, int fq) const {
;     ...
; #pragma unroll
;         for (int ai = 0; ai < 2; ++ai)
; #pragma unroll
;             for (int m = 0; m < 4; ++m) { const int rl = ai * 128 + wr * 64 + m * 16 + fr; const float rs = X[1024 + rl]; float* orow = yout + ((size_t)u.pm * 256 + rl) * DM;
; #pragma unroll
;                 for (int bj = 0; bj < 2; ++bj)
; #pragma unroll
;                     for (int n = 0; n < 2; ++n) { const int col = col0 + bj * 128 + n * 16;
;                         __builtin_nontemporal_store(acc[ai][bj][m][n] * rs * *(const f32x4*)(gn + col), (f32x4*)(orow + col)); }
;                 asm volatile("" ::: "memory"); }
;         asm volatile("s_waitcnt lgkmcnt(0)" ::: "memory"); __builtin_amdgcn_s_barrier(); asm volatile("" ::: "memory");
	v_pk_mul_f32 v[68:69], v[68:69], v[216:217] op_sel_hi:[1,0]
	v_pk_mul_f32 v[70:71], v[200:201], v[70:71]
	v_pk_mul_f32 v[68:69], v[198:199], v[68:69]
	global_store_dwordx4 v[168:169], v[68:71], off offset:512 nt
	v_pk_mul_f32 v[66:67], v[66:67], v[216:217] op_sel_hi:[1,0]
	v_pk_mul_f32 v[64:65], v[64:65], v[216:217] op_sel_hi:[1,0]
	v_pk_mul_f32 v[66:67], v[204:205], v[66:67]
	v_pk_mul_f32 v[64:65], v[202:203], v[64:65]
	global_store_dwordx4 v[168:169], v[64:67], off offset:576 nt
	s_mov_b32 s16, 0x50000
	v_lshl_add_u64 v[168:169], v[168:169], 0, s[16:17]
	s_mov_b32 s16, 0x10000
	v_pk_mul_f32 v[62:63], v[62:63], v[218:219] op_sel_hi:[1,0]
	v_pk_mul_f32 v[60:61], v[60:61], v[218:219] op_sel_hi:[1,0]
	v_pk_mul_f32 v[62:63], v[192:193], v[62:63]
	v_pk_mul_f32 v[60:61], v[190:191], v[60:61]
	global_store_dwordx4 v[168:169], v[60:63], off nt
	v_pk_mul_f32 v[58:59], v[58:59], v[218:219] op_sel_hi:[1,0]
	v_pk_mul_f32 v[56:57], v[56:57], v[218:219] op_sel_hi:[1,0]
	v_pk_mul_f32 v[58:59], v[196:197], v[58:59]
	v_pk_mul_f32 v[56:57], v[194:195], v[56:57]
	global_store_dwordx4 v[168:169], v[56:59], off offset:64 nt
	v_pk_mul_f32 v[54:55], v[54:55], v[218:219] op_sel_hi:[1,0]
	v_pk_mul_f32 v[52:53], v[52:53], v[218:219] op_sel_hi:[1,0]
	v_pk_mul_f32 v[54:55], v[200:201], v[54:55]
	v_pk_mul_f32 v[52:53], v[198:199], v[52:53]
	global_store_dwordx4 v[168:169], v[52:55], off offset:512 nt
	v_pk_mul_f32 v[50:51], v[50:51], v[218:219] op_sel_hi:[1,0]
	v_pk_mul_f32 v[48:49], v[48:49], v[218:219] op_sel_hi:[1,0]
	v_pk_mul_f32 v[50:51], v[204:205], v[50:51]
	v_pk_mul_f32 v[48:49], v[202:203], v[48:49]
	global_store_dwordx4 v[168:169], v[48:51], off offset:576 nt
	v_lshl_add_u64 v[168:169], v[168:169], 0, s[16:17]
	v_pk_mul_f32 v[46:47], v[46:47], v[220:221] op_sel_hi:[1,0]
	v_pk_mul_f32 v[44:45], v[44:45], v[220:221] op_sel_hi:[1,0]
	v_pk_mul_f32 v[46:47], v[192:193], v[46:47]
	v_pk_mul_f32 v[44:45], v[190:191], v[44:45]
	global_store_dwordx4 v[168:169], v[44:47], off nt
	v_pk_mul_f32 v[42:43], v[42:43], v[220:221] op_sel_hi:[1,0]
	v_pk_mul_f32 v[40:41], v[40:41], v[220:221] op_sel_hi:[1,0]
	v_pk_mul_f32 v[42:43], v[196:197], v[42:43]
	v_pk_mul_f32 v[40:41], v[194:195], v[40:41]
	global_store_dwordx4 v[168:169], v[40:43], off offset:64 nt
	v_pk_mul_f32 v[38:39], v[38:39], v[220:221] op_sel_hi:[1,0]
	v_pk_mul_f32 v[36:37], v[36:37], v[220:221] op_sel_hi:[1,0]
	v_pk_mul_f32 v[38:39], v[200:201], v[38:39]
	v_pk_mul_f32 v[36:37], v[198:199], v[36:37]
	global_store_dwordx4 v[168:169], v[36:39], off offset:512 nt
	v_pk_mul_f32 v[34:35], v[34:35], v[220:221] op_sel_hi:[1,0]
	v_pk_mul_f32 v[32:33], v[32:33], v[220:221] op_sel_hi:[1,0]
	v_pk_mul_f32 v[34:35], v[204:205], v[34:35]
	v_pk_mul_f32 v[32:33], v[202:203], v[32:33]
	global_store_dwordx4 v[168:169], v[32:35], off offset:576 nt
	v_lshl_add_u64 v[168:169], v[168:169], 0, s[16:17]
	v_pk_mul_f32 v[30:31], v[30:31], v[222:223] op_sel_hi:[1,0]
	v_pk_mul_f32 v[28:29], v[28:29], v[222:223] op_sel_hi:[1,0]
	v_pk_mul_f32 v[30:31], v[192:193], v[30:31]
	v_pk_mul_f32 v[28:29], v[190:191], v[28:29]
	global_store_dwordx4 v[168:169], v[28:31], off nt
	v_pk_mul_f32 v[26:27], v[26:27], v[222:223] op_sel_hi:[1,0]
	v_pk_mul_f32 v[24:25], v[24:25], v[222:223] op_sel_hi:[1,0]
	v_pk_mul_f32 v[26:27], v[196:197], v[26:27]
	v_pk_mul_f32 v[24:25], v[194:195], v[24:25]
	global_store_dwordx4 v[168:169], v[24:27], off offset:64 nt
	v_pk_mul_f32 v[22:23], v[22:23], v[222:223] op_sel_hi:[1,0]
	v_pk_mul_f32 v[20:21], v[20:21], v[222:223] op_sel_hi:[1,0]
	v_pk_mul_f32 v[22:23], v[200:201], v[22:23]
	v_pk_mul_f32 v[20:21], v[198:199], v[20:21]
	global_store_dwordx4 v[168:169], v[20:23], off offset:512 nt
	v_pk_mul_f32 v[18:19], v[18:19], v[222:223] op_sel_hi:[1,0]
	v_pk_mul_f32 v[16:17], v[16:17], v[222:223] op_sel_hi:[1,0]
	v_pk_mul_f32 v[18:19], v[204:205], v[18:19]
	v_pk_mul_f32 v[16:17], v[202:203], v[16:17]
	global_store_dwordx4 v[168:169], v[16:19], off offset:576 nt
	v_lshl_add_u64 v[168:169], v[168:169], 0, s[16:17]
	v_pk_mul_f32 v[14:15], v[14:15], v[224:225] op_sel_hi:[1,0]
	v_pk_mul_f32 v[12:13], v[12:13], v[224:225] op_sel_hi:[1,0]
	v_pk_mul_f32 v[14:15], v[192:193], v[14:15]
	v_pk_mul_f32 v[12:13], v[190:191], v[12:13]
	global_store_dwordx4 v[168:169], v[12:15], off nt
	v_pk_mul_f32 v[10:11], v[10:11], v[224:225] op_sel_hi:[1,0]
	v_pk_mul_f32 v[8:9], v[8:9], v[224:225] op_sel_hi:[1,0]
	v_pk_mul_f32 v[10:11], v[196:197], v[10:11]
	v_pk_mul_f32 v[8:9], v[194:195], v[8:9]
	global_store_dwordx4 v[168:169], v[8:11], off offset:64 nt
	v_pk_mul_f32 v[6:7], v[6:7], v[224:225] op_sel_hi:[1,0]
	v_pk_mul_f32 v[4:5], v[4:5], v[224:225] op_sel_hi:[1,0]
	v_pk_mul_f32 v[6:7], v[200:201], v[6:7]
	v_pk_mul_f32 v[4:5], v[198:199], v[4:5]
	global_store_dwordx4 v[168:169], v[4:7], off offset:512 nt
	v_pk_mul_f32 v[2:3], v[2:3], v[224:225] op_sel_hi:[1,0]
	v_pk_mul_f32 v[0:1], v[0:1], v[224:225] op_sel_hi:[1,0]
	v_pk_mul_f32 v[2:3], v[204:205], v[2:3]
	v_pk_mul_f32 v[0:1], v[202:203], v[0:1]
	global_store_dwordx4 v[168:169], v[0:3], off offset:576 nt
	s_andn2_b64 vcc, exec, s[4:5]
	s_mov_b64 s[4:5], -1
	s_waitcnt lgkmcnt(0)
	s_barrier
	s_cbranch_vccnz .LBB0_2191
	s_andn2_b64 vcc, exec, s[14:15]
	s_cbranch_vccnz .LBB0_2190
	s_barrier
	s_branch .LBB0_2190
